# v9 + s_setprio 2 around the MFMA block of the 4 GEMM k-loops
# speedup vs baseline: 1.0729x; 1.0092x over previous
; template <int EPI>
; __device__ __forceinline__ void gemm_tile(const bf16_t* __restrict__ A, const int lda, const bf16_t* __restrict__ Bt, const int ldb,
;                                           const int K, const int m0, const int n0, void* Cout, const int ldc, char* lds, const int tid) {
;     ...
;   for (int kt = 0; kt < nt; ++kt) {
;     asm volatile("s_waitcnt vmcnt(0)" ::: "memory");
;     __syncthreads();
;     if (kt + 1 < nt) stageB(kt + 1, (kt + 1) & 1);
;     const char* sa = lds + (kt & 1) * 32768;
;     const char* sb = sa + 16384;
;     bf16x8 af[2][4], bfr[2][4];
; #pragma unroll
;     for (int ks = 0; ks < 2; ++ks) {
; #pragma unroll
;       for (int m = 0; m < 4; ++m) af[ks][m] = *(const bf16x8*)(sa + (wr * 64 + m * 16 + fr) * 128 + (ks ? xk1 : xk0));
; #pragma unroll
;       for (int n = 0; n < 4; ++n) bfr[ks][n] = *(const bf16x8*)(sb + (wc * 64 + n * 16 + fr) * 128 + (ks ? xk1 : xk0));
;     }
;     if (kt + 1 < nt) stageA(kt + 1, (kt + 1) & 1);
; #pragma unroll
;     for (int ks = 0; ks < 2; ++ks)
; #pragma unroll
;       for (int m = 0; m < 4; ++m)
; #pragma unroll
;         for (int n = 0; n < 4; ++n) acc[m][n] = __builtin_amdgcn_mfma_f32_16x16x32_bf16(bfr[ks][n], af[ks][m], acc[m][n], 0, 0, 0);
;   }
.LBB0_104:
	s_add_i32 s25, s26, 0x8000
	s_and_b32 s23, s25, 0x8000
	v_add_u32_e32 v139, s23, v176
	v_add_u32_e32 v70, 0x4000, v139
	v_lshl_add_u64 v[68:69], v[140:141], 0, s[34:35]
	v_readfirstlane_b32 s27, v70
	v_add_u32_e32 v70, 0x5000, v139
	s_mov_b32 m0, s27
	v_readfirstlane_b32 s27, v70
	v_add_u32_e32 v70, 0x6000, v139
	s_waitcnt vmcnt(0)
	s_waitcnt vmcnt(0) lgkmcnt(0)
	s_barrier
	global_load_lds_dwordx4 v[68:69], off
	v_lshl_add_u64 v[68:69], v[142:143], 0, s[34:35]
	s_mov_b32 m0, s27
	v_readfirstlane_b32 s27, v70
	v_add_u32_e32 v70, 0x7000, v139
	global_load_lds_dwordx4 v[68:69], off
	v_lshl_add_u64 v[68:69], v[144:145], 0, s[34:35]
	s_mov_b32 m0, s27
	v_readfirstlane_b32 s27, v70
	global_load_lds_dwordx4 v[68:69], off
	v_lshl_add_u64 v[68:69], v[146:147], 0, s[34:35]
	s_mov_b32 m0, s27
	s_and_b32 s26, s26, 0x8000
	global_load_lds_dwordx4 v[68:69], off
	v_or_b32_e32 v68, s26, v174
	v_add_u32_e32 v69, v68, v181
	v_add_u32_e32 v68, v68, v180
	v_or_b32_e32 v72, s26, v175
	v_readfirstlane_b32 s26, v139
	v_add_u32_e32 v168, 0x1000, v139
	ds_read_b128 v[104:107], v69
	ds_read_b128 v[100:103], v69 offset:2048
	ds_read_b128 v[96:99], v69 offset:4096
	ds_read_b128 v[84:87], v69 offset:6144
	ds_read_b128 v[190:193], v68 offset:16384
	ds_read_b128 v[194:197], v68 offset:18432
	ds_read_b128 v[198:201], v68 offset:20480
	ds_read_b128 v[202:205], v68 offset:22528
	v_add_u32_e32 v68, v72, v181
	v_add_u32_e32 v76, v72, v180
	v_lshl_add_u64 v[158:159], v[148:149], 0, s[34:35]
	s_mov_b32 m0, s26
	v_readfirstlane_b32 s26, v168
	v_add_u32_e32 v168, 0x2000, v139
	ds_read_b128 v[206:209], v68
	ds_read_b128 v[210:213], v68 offset:2048
	ds_read_b128 v[92:95], v68 offset:4096
	ds_read_b128 v[68:71], v68 offset:6144
	ds_read_b128 v[88:91], v76 offset:16384
	ds_read_b128 v[80:83], v76 offset:18432
	ds_read_b128 v[72:75], v76 offset:20480
	ds_read_b128 v[76:79], v76 offset:22528
	global_load_lds_dwordx4 v[158:159], off
	v_lshl_add_u64 v[158:159], v[150:151], 0, s[34:35]
	s_mov_b32 m0, s26
	v_readfirstlane_b32 s26, v168
	v_add_u32_e32 v139, 0x3000, v139
	global_load_lds_dwordx4 v[158:159], off
	v_lshl_add_u64 v[158:159], v[152:153], 0, s[34:35]
	s_mov_b32 m0, s26
	v_readfirstlane_b32 s26, v139
	global_load_lds_dwordx4 v[158:159], off
	v_lshl_add_u64 v[158:159], v[154:155], 0, s[34:35]
	s_mov_b32 m0, s26
	s_waitcnt lgkmcnt(0)
	s_setprio 2
	v_mfma_f32_16x16x32_bf16 v[64:67], v[190:193], v[104:107], v[64:67]
	global_load_lds_dwordx4 v[158:159], off
	s_add_u32 s34, s34, 0x80
	v_mfma_f32_16x16x32_bf16 v[60:63], v[194:197], v[104:107], v[60:63]
	s_addc_u32 s35, s35, 0
	s_cmpk_eq_i32 s34, 0x1580
	s_mov_b32 s26, s25
	v_mfma_f32_16x16x32_bf16 v[56:59], v[198:201], v[104:107], v[56:59]
	v_mfma_f32_16x16x32_bf16 v[52:55], v[202:205], v[104:107], v[52:55]
	v_mfma_f32_16x16x32_bf16 v[36:39], v[190:193], v[100:103], v[36:39]
	v_mfma_f32_16x16x32_bf16 v[28:31], v[194:197], v[100:103], v[28:31]
	v_mfma_f32_16x16x32_bf16 v[20:23], v[198:201], v[100:103], v[20:23]
	v_mfma_f32_16x16x32_bf16 v[24:27], v[202:205], v[100:103], v[24:27]
	v_mfma_f32_16x16x32_bf16 v[8:11], v[190:193], v[96:99], v[8:11]
	v_mfma_f32_16x16x32_bf16 v[16:19], v[194:197], v[96:99], v[16:19]
	v_mfma_f32_16x16x32_bf16 v[32:35], v[198:201], v[96:99], v[32:35]
	v_mfma_f32_16x16x32_bf16 v[48:51], v[202:205], v[96:99], v[48:51]
	v_mfma_f32_16x16x32_bf16 v[44:47], v[190:193], v[84:87], v[44:47]
	v_mfma_f32_16x16x32_bf16 v[40:43], v[194:197], v[84:87], v[40:43]
	v_mfma_f32_16x16x32_bf16 v[12:15], v[198:201], v[84:87], v[12:15]
	v_mfma_f32_16x16x32_bf16 v[4:7], v[202:205], v[84:87], v[4:7]
	v_mfma_f32_16x16x32_bf16 v[64:67], v[88:91], v[206:209], v[64:67]
	v_mfma_f32_16x16x32_bf16 v[60:63], v[80:83], v[206:209], v[60:63]
	v_mfma_f32_16x16x32_bf16 v[56:59], v[72:75], v[206:209], v[56:59]
	v_mfma_f32_16x16x32_bf16 v[52:55], v[76:79], v[206:209], v[52:55]
	v_mfma_f32_16x16x32_bf16 v[36:39], v[88:91], v[210:213], v[36:39]
	v_mfma_f32_16x16x32_bf16 v[28:31], v[80:83], v[210:213], v[28:31]
	v_mfma_f32_16x16x32_bf16 v[20:23], v[72:75], v[210:213], v[20:23]
	v_mfma_f32_16x16x32_bf16 v[24:27], v[76:79], v[210:213], v[24:27]
	v_mfma_f32_16x16x32_bf16 v[8:11], v[88:91], v[92:95], v[8:11]
	v_mfma_f32_16x16x32_bf16 v[16:19], v[80:83], v[92:95], v[16:19]
	v_mfma_f32_16x16x32_bf16 v[32:35], v[72:75], v[92:95], v[32:35]
	v_mfma_f32_16x16x32_bf16 v[48:51], v[76:79], v[92:95], v[48:51]
	v_mfma_f32_16x16x32_bf16 v[44:47], v[88:91], v[68:71], v[44:47]
	v_mfma_f32_16x16x32_bf16 v[40:43], v[80:83], v[68:71], v[40:43]
	v_mfma_f32_16x16x32_bf16 v[12:15], v[72:75], v[68:71], v[12:15]
	v_mfma_f32_16x16x32_bf16 v[4:7], v[76:79], v[68:71], v[4:7]
	s_setprio 0
	s_cbranch_scc0 .LBB0_104
	v_add_u32_e32 v84, s23, v174
	v_add_u32_e32 v80, v84, v181
	s_waitcnt vmcnt(0)
	s_waitcnt vmcnt(0) lgkmcnt(0)
	s_barrier
; template <int EPI>
; __device__ __forceinline__ void gemm_tile(const bf16_t* __restrict__ A, const int lda, const bf16_t* __restrict__ Bt, const int ldb,
;                                           const int K, const int m0, const int n0, void* Cout, const int ldc, char* lds, const int tid) {
;     ...
; #pragma unroll
;     for (int ks = 0; ks < 2; ++ks)
; #pragma unroll
;       for (int m = 0; m < 4; ++m)
; #pragma unroll
;         for (int n = 0; n < 4; ++n) acc[m][n] = __builtin_amdgcn_mfma_f32_16x16x32_bf16(bfr[ks][n], af[ks][m], acc[m][n], 0, 0, 0);
;   }
;   if (EPI == EPI_RESID) {
;     float* C0 = (float*)Cout + (size_t)(m0 + wr * 64 + fr) * ldc + n0 + wc * 64 + fq * 4;
; #pragma unroll
;     for (int mh = 0; mh < 2; ++mh) {
;       f32x4 xin[2][4];
; #pragma unroll
;       for (int m = 0; m < 2; ++m)
; #pragma unroll
;         for (int n = 0; n < 4; ++n) xin[m][n] = *(const f32x4*)(C0 + (size_t)(mh * 2 + m) * 16 * ldc + n * 16);
	ds_read_b128 v[68:71], v80
	ds_read_b128 v[72:75], v80 offset:2048
	ds_read_b128 v[76:79], v80 offset:4096
	ds_read_b128 v[80:83], v80 offset:6144
	v_add_u32_e32 v96, v84, v180
	ds_read_b128 v[84:87], v96 offset:16384
	ds_read_b128 v[88:91], v96 offset:18432
	ds_read_b128 v[92:95], v96 offset:20480
	ds_read_b128 v[96:99], v96 offset:22528
	v_add_u32_e32 v139, s23, v175
	v_add_u32_e32 v144, v139, v181
	s_waitcnt lgkmcnt(3)
	v_mfma_f32_16x16x32_bf16 v[36:39], v[84:87], v[72:75], v[36:39]
	ds_read_b128 v[100:103], v144
	ds_read_b128 v[104:107], v144 offset:2048
	ds_read_b128 v[140:143], v144 offset:4096
	ds_read_b128 v[144:147], v144 offset:6144
	v_add_u32_e32 v139, v139, v180
	ds_read_b128 v[148:151], v139 offset:16384
	ds_read_b128 v[152:155], v139 offset:18432
	ds_read_b128 v[190:193], v139 offset:20480
	ds_read_b128 v[194:197], v139 offset:22528
	v_mfma_f32_16x16x32_bf16 v[64:67], v[84:87], v[68:71], v[64:67]
	v_readlane_b32 s26, v253, 25
	v_readlane_b32 s27, v253, 26
	v_mov_b32_e32 v139, v3
	s_waitcnt lgkmcnt(10)
	v_mfma_f32_16x16x32_bf16 v[60:63], v[88:91], v[68:71], v[60:63]
	s_add_i32 s24, s24, s0
	s_waitcnt lgkmcnt(9)
	v_mfma_f32_16x16x32_bf16 v[56:59], v[92:95], v[68:71], v[56:59]
	s_waitcnt lgkmcnt(8)
	v_mfma_f32_16x16x32_bf16 v[52:55], v[96:99], v[68:71], v[52:55]
	v_mfma_f32_16x16x32_bf16 v[8:11], v[84:87], v[76:79], v[8:11]
	v_mfma_f32_16x16x32_bf16 v[16:19], v[88:91], v[76:79], v[16:19]
	v_mfma_f32_16x16x32_bf16 v[68:71], v[92:95], v[76:79], v[32:35]
	v_mfma_f32_16x16x32_bf16 v[48:51], v[96:99], v[76:79], v[48:51]
	s_waitcnt lgkmcnt(3)
	v_mfma_f32_16x16x32_bf16 v[76:79], v[148:151], v[104:107], v[36:39]
	s_nop 2
	v_add_u32_e32 v36, s3, v182
	v_ashrrev_i32_e32 v37, 31, v36
	v_lshlrev_b64 v[36:37], 12, v[36:37]
	v_mfma_f32_16x16x32_bf16 v[20:23], v[92:95], v[72:75], v[20:23]
	v_lshl_add_u64 v[36:37], s[26:27], 0, v[36:37]
	s_ashr_i32 s3, s2, 31
	v_lshl_add_u64 v[36:37], s[2:3], 2, v[36:37]
	v_mfma_f32_16x16x32_bf16 v[28:31], v[88:91], v[72:75], v[28:31]
	v_lshl_add_u64 v[36:37], v[36:37], 0, v[2:3]
	v_lshl_add_u64 v[36:37], v[36:37], 0, v[138:139]
	s_mov_b32 s2, 0x10000
	v_mfma_f32_16x16x32_bf16 v[24:27], v[96:99], v[72:75], v[24:27]
	s_cmpk_gt_i32 s24, 0x427
	v_mfma_f32_16x16x32_bf16 v[44:47], v[84:87], v[80:83], v[44:47]
	v_mfma_f32_16x16x32_bf16 v[40:43], v[88:91], v[80:83], v[40:43]
	v_mfma_f32_16x16x32_bf16 v[72:75], v[92:95], v[80:83], v[12:15]
	s_waitcnt lgkmcnt(1)
	v_mfma_f32_16x16x32_bf16 v[84:87], v[190:193], v[104:107], v[20:23]
	s_waitcnt lgkmcnt(0)
	v_mfma_f32_16x16x32_bf16 v[20:23], v[194:197], v[140:143], v[48:51]
	s_nop 2
	v_add_co_u32_e32 v50, vcc, s2, v36
	v_mfma_f32_16x16x32_bf16 v[4:7], v[96:99], v[80:83], v[4:7]
	s_nop 0
	v_addc_co_u32_e32 v51, vcc, 0, v37, vcc
	s_mov_b32 s2, 0x20000
	v_mfma_f32_16x16x32_bf16 v[64:67], v[148:151], v[100:103], v[64:67]
	v_mfma_f32_16x16x32_bf16 v[60:63], v[152:155], v[100:103], v[60:63]
	v_mfma_f32_16x16x32_bf16 v[56:59], v[190:193], v[100:103], v[56:59]
	v_mfma_f32_16x16x32_bf16 v[52:55], v[194:197], v[100:103], v[52:55]
	v_mfma_f32_16x16x32_bf16 v[80:83], v[152:155], v[104:107], v[28:31]
	v_mfma_f32_16x16x32_bf16 v[88:91], v[194:197], v[104:107], v[24:27]
	v_mfma_f32_16x16x32_bf16 v[32:35], v[148:151], v[140:143], v[8:11]
	v_mfma_f32_16x16x32_bf16 v[28:31], v[152:155], v[140:143], v[16:19]
	v_mfma_f32_16x16x32_bf16 v[24:27], v[190:193], v[140:143], v[68:71]
	v_mfma_f32_16x16x32_bf16 v[16:19], v[148:151], v[144:147], v[44:47]
	v_mfma_f32_16x16x32_bf16 v[12:15], v[152:155], v[144:147], v[40:43]
	s_nop 2
	global_load_dwordx4 v[38:41], v[36:37], off
	global_load_dwordx4 v[42:45], v[36:37], off offset:64
	global_load_dwordx4 v[46:49], v[36:37], off offset:128
	global_load_dwordx4 v[68:71], v[36:37], off offset:192
	v_mfma_f32_16x16x32_bf16 v[8:11], v[190:193], v[144:147], v[72:75]
	s_nop 2
	global_load_dwordx4 v[72:75], v[50:51], off
	global_load_dwordx4 v[92:95], v[50:51], off offset:64
	global_load_dwordx4 v[96:99], v[50:51], off offset:128
	global_load_dwordx4 v[100:103], v[50:51], off offset:192
	s_waitcnt vmcnt(7)
; template <int EPI>
; __device__ __forceinline__ void gemm_tile(const bf16_t* __restrict__ A, const int lda, const bf16_t* __restrict__ Bt, const int ldb,
;                                           const int K, const int m0, const int n0, void* Cout, const int ldc, char* lds, const int tid) {
;     ...
;   if (EPI == EPI_RESID) {
;     float* C0 = (float*)Cout + (size_t)(m0 + wr * 64 + fr) * ldc + n0 + wc * 64 + fq * 4;
; #pragma unroll
;     for (int mh = 0; mh < 2; ++mh) {
;       f32x4 xin[2][4];
; #pragma unroll
;       for (int m = 0; m < 2; ++m)
; #pragma unroll
;         for (int n = 0; n < 4; ++n) xin[m][n] = *(const f32x4*)(C0 + (size_t)(mh * 2 + m) * 16 * ldc + n * 16);
; #pragma unroll
;       for (int m = 0; m < 2; ++m)
; #pragma unroll
;         for (int n = 0; n < 4; ++n) asm volatile("" : "+v"(xin[m][n]));
; #pragma unroll
;       for (int m = 0; m < 2; ++m)
; #pragma unroll
;         for (int n = 0; n < 4; ++n) *(f32x4*)(C0 + (size_t)(mh * 2 + m) * 16 * ldc + n * 16) = xin[m][n] * ALPHA + acc[mh * 2 + m][n];
;     }
	s_nop 0
	v_pk_fma_f32 v[40:41], v[40:41], s[78:79], v[66:67] op_sel_hi:[1,0,1]
	v_pk_fma_f32 v[38:39], v[38:39], s[78:79], v[64:65] op_sel_hi:[1,0,1]
	s_waitcnt vmcnt(6)
	s_waitcnt vmcnt(5)
	s_waitcnt vmcnt(4)
	s_waitcnt vmcnt(3)
	s_waitcnt vmcnt(2)
	s_waitcnt vmcnt(1)
	s_waitcnt vmcnt(0)
	global_store_dwordx4 v[36:37], v[38:41], off
	v_mfma_f32_16x16x32_bf16 v[4:7], v[194:197], v[144:147], v[4:7]
	s_nop 0
	v_fma_f32 v40, v44, s78, v62
	v_fma_f32 v41, v45, s78, v63
	v_pk_fma_f32 v[38:39], v[42:43], s[78:79], v[60:61] op_sel_hi:[1,0,1]
	global_store_dwordx4 v[36:37], v[38:41], off offset:64
	s_nop 1
	v_pk_fma_f32 v[40:41], v[48:49], s[78:79], v[58:59] op_sel_hi:[1,0,1]
	v_pk_fma_f32 v[38:39], v[46:47], s[78:79], v[56:57] op_sel_hi:[1,0,1]
	global_store_dwordx4 v[36:37], v[38:41], off offset:128
	s_nop 1
	v_pk_fma_f32 v[40:41], v[70:71], s[78:79], v[54:55] op_sel_hi:[1,0,1]
	v_pk_fma_f32 v[38:39], v[68:69], s[78:79], v[52:53] op_sel_hi:[1,0,1]
	global_store_dwordx4 v[36:37], v[38:41], off offset:192
	v_add_co_u32_e32 v70, vcc, s2, v36
	s_nop 0
	v_pk_fma_f32 v[40:41], v[74:75], s[78:79], v[78:79] op_sel_hi:[1,0,1]
	v_pk_fma_f32 v[38:39], v[72:73], s[78:79], v[76:77] op_sel_hi:[1,0,1]
	global_store_dwordx4 v[50:51], v[38:41], off
	v_addc_co_u32_e32 v71, vcc, 0, v37, vcc
	s_nop 0
	v_pk_fma_f32 v[40:41], v[94:95], s[78:79], v[82:83] op_sel_hi:[1,0,1]
	v_pk_fma_f32 v[38:39], v[92:93], s[78:79], v[80:81] op_sel_hi:[1,0,1]
	global_store_dwordx4 v[50:51], v[38:41], off offset:64
	s_mov_b32 s2, 0x30000
	v_add_co_u32_e32 v36, vcc, s2, v36
	v_pk_fma_f32 v[40:41], v[98:99], s[78:79], v[86:87] op_sel_hi:[1,0,1]
	v_pk_fma_f32 v[38:39], v[96:97], s[78:79], v[84:85] op_sel_hi:[1,0,1]
	global_store_dwordx4 v[50:51], v[38:41], off offset:128
	v_addc_co_u32_e32 v37, vcc, 0, v37, vcc
	s_nop 0
	v_pk_fma_f32 v[40:41], v[102:103], s[78:79], v[90:91] op_sel_hi:[1,0,1]
	v_pk_fma_f32 v[38:39], v[100:101], s[78:79], v[88:89] op_sel_hi:[1,0,1]
	global_store_dwordx4 v[50:51], v[38:41], off offset:192
	global_load_dwordx4 v[38:41], v[70:71], off
	s_nop 0
	global_load_dwordx4 v[42:45], v[70:71], off offset:64
	global_load_dwordx4 v[46:49], v[70:71], off offset:128
	global_load_dwordx4 v[50:53], v[70:71], off offset:192
	global_load_dwordx4 v[54:57], v[36:37], off
	global_load_dwordx4 v[58:61], v[36:37], off offset:64
	global_load_dwordx4 v[62:65], v[36:37], off offset:128
	global_load_dwordx4 v[66:69], v[36:37], off offset:192
	s_waitcnt vmcnt(7)
	s_waitcnt vmcnt(6)
	s_waitcnt vmcnt(5)
	s_waitcnt vmcnt(4)
	s_waitcnt vmcnt(3)
	s_waitcnt vmcnt(2)
	s_waitcnt vmcnt(1)
	s_waitcnt vmcnt(0)
	v_pk_fma_f32 v[34:35], v[40:41], s[78:79], v[34:35] op_sel_hi:[1,0,1]
	v_pk_fma_f32 v[32:33], v[38:39], s[78:79], v[32:33] op_sel_hi:[1,0,1]
	v_pk_fma_f32 v[30:31], v[44:45], s[78:79], v[30:31] op_sel_hi:[1,0,1]
	v_pk_fma_f32 v[28:29], v[42:43], s[78:79], v[28:29] op_sel_hi:[1,0,1]
	v_pk_fma_f32 v[26:27], v[48:49], s[78:79], v[26:27] op_sel_hi:[1,0,1]
	v_pk_fma_f32 v[24:25], v[46:47], s[78:79], v[24:25] op_sel_hi:[1,0,1]
	v_pk_fma_f32 v[22:23], v[52:53], s[78:79], v[22:23] op_sel_hi:[1,0,1]
	v_pk_fma_f32 v[20:21], v[50:51], s[78:79], v[20:21] op_sel_hi:[1,0,1]
	v_pk_fma_f32 v[18:19], v[56:57], s[78:79], v[18:19] op_sel_hi:[1,0,1]
	v_pk_fma_f32 v[16:17], v[54:55], s[78:79], v[16:17] op_sel_hi:[1,0,1]
	v_pk_fma_f32 v[14:15], v[60:61], s[78:79], v[14:15] op_sel_hi:[1,0,1]
	v_pk_fma_f32 v[12:13], v[58:59], s[78:79], v[12:13] op_sel_hi:[1,0,1]
	v_pk_fma_f32 v[10:11], v[64:65], s[78:79], v[10:11] op_sel_hi:[1,0,1]
	v_pk_fma_f32 v[8:9], v[62:63], s[78:79], v[8:9] op_sel_hi:[1,0,1]
	v_pk_fma_f32 v[6:7], v[68:69], s[78:79], v[6:7] op_sel_hi:[1,0,1]
	v_pk_fma_f32 v[4:5], v[66:67], s[78:79], v[4:5] op_sel_hi:[1,0,1]
	global_store_dwordx4 v[70:71], v[32:35], off
	global_store_dwordx4 v[70:71], v[28:31], off offset:64
	global_store_dwordx4 v[70:71], v[24:27], off offset:128
	global_store_dwordx4 v[70:71], v[20:23], off offset:192
	global_store_dwordx4 v[36:37], v[16:19], off
	global_store_dwordx4 v[36:37], v[12:15], off offset:64
	global_store_dwordx4 v[36:37], v[8:11], off offset:128
	global_store_dwordx4 v[36:37], v[4:7], off offset:192
	s_cbranch_scc0 .LBB0_103

; template <int EPI>
; __device__ __forceinline__ void gemm_tile(const bf16_t* __restrict__ A, const int lda, const bf16_t* __restrict__ Bt, const int ldb,
;                                           const int K, const int m0, const int n0, void* Cout, const int ldc, char* lds, const int tid) {
;     ...
;   for (int kt = 0; kt < nt; ++kt) {
;     asm volatile("s_waitcnt vmcnt(0)" ::: "memory");
;     __syncthreads();
;     if (kt + 1 < nt) stageB(kt + 1, (kt + 1) & 1);
;     const char* sa = lds + (kt & 1) * 32768;
;     const char* sb = sa + 16384;
;     bf16x8 af[2][4], bfr[2][4];
; #pragma unroll
;     for (int ks = 0; ks < 2; ++ks) {
; #pragma unroll
;       for (int m = 0; m < 4; ++m) af[ks][m] = *(const bf16x8*)(sa + (wr * 64 + m * 16 + fr) * 128 + (ks ? xk1 : xk0));
; #pragma unroll
;       for (int n = 0; n < 4; ++n) bfr[ks][n] = *(const bf16x8*)(sb + (wc * 64 + n * 16 + fr) * 128 + (ks ? xk1 : xk0));
;     }
;     if (kt + 1 < nt) stageA(kt + 1, (kt + 1) & 1);
; #pragma unroll
;     for (int ks = 0; ks < 2; ++ks)
; #pragma unroll
;       for (int m = 0; m < 4; ++m)
; #pragma unroll
;         for (int n = 0; n < 4; ++n) acc[m][n] = __builtin_amdgcn_mfma_f32_16x16x32_bf16(bfr[ks][n], af[ks][m], acc[m][n], 0, 0, 0);
;   }
.LBB0_111:
	s_add_i32 s26, s27, 0x8000
	s_and_b32 s29, s26, 0x8000
	v_add_u32_e32 v2, s29, v177
	v_add_u32_e32 v70, 0x4000, v2
	v_lshl_add_u64 v[68:69], v[140:141], 0, s[2:3]
	v_readfirstlane_b32 s29, v70
	v_add_u32_e32 v70, 0x5000, v2
	s_mov_b32 m0, s29
	v_readfirstlane_b32 s29, v70
	v_add_u32_e32 v70, 0x6000, v2
	s_waitcnt vmcnt(0)
	s_waitcnt vmcnt(0) lgkmcnt(0)
	s_barrier
	global_load_lds_dwordx4 v[68:69], off
	v_lshl_add_u64 v[68:69], v[142:143], 0, s[2:3]
	s_mov_b32 m0, s29
	v_readfirstlane_b32 s29, v70
	v_add_u32_e32 v70, 0x7000, v2
	global_load_lds_dwordx4 v[68:69], off
	v_lshl_add_u64 v[68:69], v[144:145], 0, s[2:3]
	s_mov_b32 m0, s29
	v_readfirstlane_b32 s29, v70
	global_load_lds_dwordx4 v[68:69], off
	v_lshl_add_u64 v[68:69], v[146:147], 0, s[2:3]
	s_mov_b32 m0, s29
	s_and_b32 s27, s27, 0x8000
	global_load_lds_dwordx4 v[68:69], off
	v_or_b32_e32 v68, s27, v175
	v_add_u32_e32 v69, v68, v182
	v_add_u32_e32 v68, v68, v181
	v_or_b32_e32 v72, s27, v176
	v_readfirstlane_b32 s27, v2
	v_add_u32_e32 v168, 0x1000, v2
	ds_read_b128 v[104:107], v69
	ds_read_b128 v[100:103], v69 offset:2048
	ds_read_b128 v[96:99], v69 offset:4096
	ds_read_b128 v[84:87], v69 offset:6144
	ds_read_b128 v[184:187], v68 offset:16384
	ds_read_b128 v[188:191], v68 offset:18432
	ds_read_b128 v[192:195], v68 offset:20480
	ds_read_b128 v[196:199], v68 offset:22528
	v_add_u32_e32 v68, v72, v182
	v_add_u32_e32 v76, v72, v181
	v_lshl_add_u64 v[158:159], v[148:149], 0, s[2:3]
	s_mov_b32 m0, s27
	v_readfirstlane_b32 s27, v168
	v_add_u32_e32 v168, 0x2000, v2
	ds_read_b128 v[200:203], v68
	ds_read_b128 v[204:207], v68 offset:2048
	ds_read_b128 v[92:95], v68 offset:4096
	ds_read_b128 v[68:71], v68 offset:6144
	ds_read_b128 v[88:91], v76 offset:16384
	ds_read_b128 v[80:83], v76 offset:18432
	ds_read_b128 v[72:75], v76 offset:20480
	ds_read_b128 v[76:79], v76 offset:22528
	global_load_lds_dwordx4 v[158:159], off
	v_lshl_add_u64 v[158:159], v[150:151], 0, s[2:3]
	s_mov_b32 m0, s27
	v_readfirstlane_b32 s27, v168
	v_add_u32_e32 v2, 0x3000, v2
	global_load_lds_dwordx4 v[158:159], off
	v_lshl_add_u64 v[158:159], v[152:153], 0, s[2:3]
	s_mov_b32 m0, s27
	v_readfirstlane_b32 s27, v2
	global_load_lds_dwordx4 v[158:159], off
	v_lshl_add_u64 v[158:159], v[154:155], 0, s[2:3]
	s_mov_b32 m0, s27
	s_waitcnt lgkmcnt(0)
	s_setprio 2
	v_mfma_f32_16x16x32_bf16 v[64:67], v[184:187], v[104:107], v[64:67]
	global_load_lds_dwordx4 v[158:159], off
	s_add_u32 s2, s2, 0x80
	v_mfma_f32_16x16x32_bf16 v[60:63], v[188:191], v[104:107], v[60:63]
	s_addc_u32 s3, s3, 0
	s_cmpk_lg_i32 s2, 0x780
	s_mov_b32 s27, s26
	v_mfma_f32_16x16x32_bf16 v[56:59], v[192:195], v[104:107], v[56:59]
	v_mfma_f32_16x16x32_bf16 v[52:55], v[196:199], v[104:107], v[52:55]
	v_mfma_f32_16x16x32_bf16 v[48:51], v[184:187], v[100:103], v[48:51]
	v_mfma_f32_16x16x32_bf16 v[44:47], v[188:191], v[100:103], v[44:47]
	v_mfma_f32_16x16x32_bf16 v[36:39], v[192:195], v[100:103], v[36:39]
	v_mfma_f32_16x16x32_bf16 v[40:43], v[196:199], v[100:103], v[40:43]
	v_mfma_f32_16x16x32_bf16 v[32:35], v[184:187], v[96:99], v[32:35]
	v_mfma_f32_16x16x32_bf16 v[24:27], v[188:191], v[96:99], v[24:27]
	v_mfma_f32_16x16x32_bf16 v[28:31], v[192:195], v[96:99], v[28:31]
	v_mfma_f32_16x16x32_bf16 v[20:23], v[196:199], v[96:99], v[20:23]
	v_mfma_f32_16x16x32_bf16 v[16:19], v[184:187], v[84:87], v[16:19]
	v_mfma_f32_16x16x32_bf16 v[12:15], v[188:191], v[84:87], v[12:15]
	v_mfma_f32_16x16x32_bf16 v[8:11], v[192:195], v[84:87], v[8:11]
	v_mfma_f32_16x16x32_bf16 v[4:7], v[196:199], v[84:87], v[4:7]
	v_mfma_f32_16x16x32_bf16 v[64:67], v[88:91], v[200:203], v[64:67]
	v_mfma_f32_16x16x32_bf16 v[60:63], v[80:83], v[200:203], v[60:63]
	v_mfma_f32_16x16x32_bf16 v[56:59], v[72:75], v[200:203], v[56:59]
	v_mfma_f32_16x16x32_bf16 v[52:55], v[76:79], v[200:203], v[52:55]
	v_mfma_f32_16x16x32_bf16 v[48:51], v[88:91], v[204:207], v[48:51]
	v_mfma_f32_16x16x32_bf16 v[44:47], v[80:83], v[204:207], v[44:47]
	v_mfma_f32_16x16x32_bf16 v[36:39], v[72:75], v[204:207], v[36:39]
	v_mfma_f32_16x16x32_bf16 v[40:43], v[76:79], v[204:207], v[40:43]
	v_mfma_f32_16x16x32_bf16 v[32:35], v[88:91], v[92:95], v[32:35]
	v_mfma_f32_16x16x32_bf16 v[24:27], v[80:83], v[92:95], v[24:27]
	v_mfma_f32_16x16x32_bf16 v[28:31], v[72:75], v[92:95], v[28:31]
	v_mfma_f32_16x16x32_bf16 v[20:23], v[76:79], v[92:95], v[20:23]
	v_mfma_f32_16x16x32_bf16 v[16:19], v[88:91], v[68:71], v[16:19]
	v_mfma_f32_16x16x32_bf16 v[12:15], v[80:83], v[68:71], v[12:15]
	v_mfma_f32_16x16x32_bf16 v[8:11], v[72:75], v[68:71], v[8:11]
	v_mfma_f32_16x16x32_bf16 v[4:7], v[76:79], v[68:71], v[4:7]
	s_setprio 0
	s_cbranch_scc1 .LBB0_111
	v_add_u32_e32 v2, v175, v181
	s_waitcnt vmcnt(0)
	s_waitcnt vmcnt(0) lgkmcnt(0)
	s_barrier
; __device__ __forceinline__ unsigned pk2(float lo, float hi) { const f32x2_t v = {lo, hi}; const bf16x2_t b = __builtin_convertvector(v, bf16x2_t); return __builtin_bit_cast(unsigned, b); }
; __device__ __forceinline__ float siluf_(float x) { return x * __builtin_amdgcn_rcpf(1.0f + __expf(-x)); }
; template <int EPI>
; __device__ __forceinline__ void gemm_tile(const bf16_t* __restrict__ A, const int lda, const bf16_t* __restrict__ Bt, const int ldb,
;                                           const int K, const int m0, const int n0, void* Cout, const int ldc, char* lds, const int tid) {
;     ...
; #pragma unroll
;     for (int ks = 0; ks < 2; ++ks)
; #pragma unroll
;       for (int m = 0; m < 4; ++m)
; #pragma unroll
;         for (int n = 0; n < 4; ++n) acc[m][n] = __builtin_amdgcn_mfma_f32_16x16x32_bf16(bfr[ks][n], af[ks][m], acc[m][n], 0, 0, 0);
;   }
;     ...
;     } else {
;       bf16_t* C = (bf16_t*)Cout + (size_t)row * ldc + (n0 >> 1) + wc * 32 + fq * 8;
;       const f32x4 g0 = acc[m][0], u0 = acc[m][1], g1 = acc[m][2], u1 = acc[m][3];
;       uint4 o; o.x = pk2(siluf_(g0[0]) * u0[0], siluf_(g0[1]) * u0[1]); o.y = pk2(siluf_(g0[2]) * u0[2], siluf_(g0[3]) * u0[3]);
;       o.z = pk2(siluf_(g1[0]) * u1[0], siluf_(g1[1]) * u1[1]); o.w = pk2(siluf_(g1[2]) * u1[2], siluf_(g1[3]) * u1[3]);
;       *(uint4*)C = o;
	ds_read_b128 v[68:71], v2 offset:49152
	v_add_u32_e32 v92, v175, v182
	ds_read_b128 v[72:75], v2 offset:51200
	ds_read_b128 v[76:79], v92 offset:32768
	ds_read_b128 v[80:83], v92 offset:34816
	ds_read_b128 v[84:87], v2 offset:53248
	ds_read_b128 v[88:91], v2 offset:55296
	v_add_u32_e32 v2, v176, v182
	s_waitcnt lgkmcnt(3)
	v_mfma_f32_16x16x32_bf16 v[64:67], v[68:71], v[76:79], v[64:67]
	s_lshl_b32 s2, s24, 6
	s_ashr_i32 s3, s2, 31
	s_movk_i32 s24, 0x1600
	v_mfma_f32_16x16x32_bf16 v[60:63], v[72:75], v[76:79], v[60:63]
	s_add_i32 s23, s23, s0
	s_cmpk_gt_i32 s23, 0x16db
	s_waitcnt lgkmcnt(1)
	v_mfma_f32_16x16x32_bf16 v[56:59], v[84:87], v[76:79], v[56:59]
	s_waitcnt lgkmcnt(0)
	v_mfma_f32_16x16x32_bf16 v[52:55], v[88:91], v[76:79], v[52:55]
	ds_read_b128 v[76:79], v92 offset:36864
	ds_read_b128 v[92:95], v92 offset:38912
	ds_read_b128 v[96:99], v2 offset:32768
	ds_read_b128 v[100:103], v2 offset:34816
	ds_read_b128 v[104:107], v2 offset:36864
	ds_read_b128 v[140:143], v2 offset:38912
	v_add_u32_e32 v2, v176, v181
	ds_read_b128 v[144:147], v2 offset:49152
	ds_read_b128 v[148:151], v2 offset:51200
	s_waitcnt lgkmcnt(1)
	v_mfma_f32_16x16x32_bf16 v[64:67], v[144:147], v[96:99], v[64:67]
	v_mfma_f32_16x16x32_bf16 v[184:187], v[68:71], v[76:79], v[32:35]
	s_nop 6
	v_mul_f32_e32 v34, 0xbfb8aa3b, v64
	v_mul_f32_e32 v35, 0xbfb8aa3b, v65
	v_exp_f32_e32 v34, v34
	v_exp_f32_e32 v35, v35
	s_waitcnt lgkmcnt(0)
	v_mfma_f32_16x16x32_bf16 v[60:63], v[148:151], v[96:99], v[60:63]
	v_lshl_add_u64 v[32:33], s[2:3], 1, v[134:135]
	v_add_f32_e32 v34, 1.0, v34
	v_add_f32_e32 v35, 1.0, v35
	v_rcp_f32_e32 v34, v34
	v_rcp_f32_e32 v35, v35
	v_mfma_f32_16x16x32_bf16 v[48:51], v[68:71], v[80:83], v[48:51]
	v_mul_f32_e64 v34, v64, v34
	v_mul_f32_e64 v35, v65, v35
	v_mfma_f32_16x16x32_bf16 v[44:47], v[72:75], v[80:83], v[44:47]
	v_mul_f32_e64 v34, v60, v34
	v_mul_f32_e64 v35, v61, v35
	v_mul_f32_e32 v60, 0xbfb8aa3b, v67
	v_cvt_pk_bf16_f32 v34, v34, v35
	v_mfma_f32_16x16x32_bf16 v[36:39], v[84:87], v[80:83], v[36:39]
	v_mul_f32_e32 v35, 0xbfb8aa3b, v66
	v_exp_f32_e32 v35, v35
	v_exp_f32_e32 v61, v60
	v_mfma_f32_16x16x32_bf16 v[40:43], v[88:91], v[80:83], v[40:43]
	ds_read_b128 v[80:83], v2 offset:53248
	ds_read_b128 v[152:155], v2 offset:55296
	v_add_f32_e32 v35, 1.0, v35
	v_rcp_f32_e32 v60, v35
	s_waitcnt lgkmcnt(1)
	v_mfma_f32_16x16x32_bf16 v[56:59], v[80:83], v[96:99], v[56:59]
	v_add_f32_e32 v35, 1.0, v61
	v_rcp_f32_e32 v61, v35
	v_or_b32_e32 v2, s25, v131
	s_waitcnt lgkmcnt(0)
; __device__ __forceinline__ unsigned pk2(float lo, float hi) { const f32x2_t v = {lo, hi}; const bf16x2_t b = __builtin_convertvector(v, bf16x2_t); return __builtin_bit_cast(unsigned, b); }
; __device__ __forceinline__ float siluf_(float x) { return x * __builtin_amdgcn_rcpf(1.0f + __expf(-x)); }
; template <int EPI>
; __device__ __forceinline__ void gemm_tile(const bf16_t* __restrict__ A, const int lda, const bf16_t* __restrict__ Bt, const int ldb,
;                                           const int K, const int m0, const int n0, void* Cout, const int ldc, char* lds, const int tid) {
;     ...
;     } else {
;       bf16_t* C = (bf16_t*)Cout + (size_t)row * ldc + (n0 >> 1) + wc * 32 + fq * 8;
;       const f32x4 g0 = acc[m][0], u0 = acc[m][1], g1 = acc[m][2], u1 = acc[m][3];
;       uint4 o; o.x = pk2(siluf_(g0[0]) * u0[0], siluf_(g0[1]) * u0[1]); o.y = pk2(siluf_(g0[2]) * u0[2], siluf_(g0[3]) * u0[3]);
;       o.z = pk2(siluf_(g1[0]) * u1[0], siluf_(g1[1]) * u1[1]); o.w = pk2(siluf_(g1[2]) * u1[2], siluf_(g1[3]) * u1[3]);
;       *(uint4*)C = o;
	v_mfma_f32_16x16x32_bf16 v[52:55], v[152:155], v[96:99], v[52:55]
	s_nop 2
	v_mul_f32_e32 v35, 0xbfb8aa3b, v56
	v_exp_f32_e32 v35, v35
	v_mul_f32_e32 v64, 0xbfb8aa3b, v57
	v_exp_f32_e32 v65, v64
	v_pk_mul_f32 v[60:61], v[66:67], v[60:61]
	v_add_f32_e32 v35, 1.0, v35
	v_rcp_f32_e32 v64, v35
	v_add_f32_e32 v35, 1.0, v65
	v_rcp_f32_e32 v65, v35
	v_pk_mul_f32 v[60:61], v[62:63], v[60:61]
	v_mfma_f32_16x16x32_bf16 v[48:51], v[144:147], v[100:103], v[48:51]
	v_cvt_pk_bf16_f32 v35, v60, v61
	v_mul_f32_e32 v60, 0xbfb8aa3b, v58
	v_exp_f32_e32 v60, v60
	v_mul_f32_e32 v61, 0xbfb8aa3b, v59
	v_pk_mul_f32 v[56:57], v[56:57], v[64:65]
	v_exp_f32_e32 v65, v61
	v_add_f32_e32 v60, 1.0, v60
	v_rcp_f32_e32 v64, v60
	v_mfma_f32_16x16x32_bf16 v[60:63], v[80:83], v[100:103], v[36:39]
	v_add_u32_e32 v2, v2, v183
	v_mad_i64_i32 v[158:159], s[2:3], v2, s24, v[32:33]
	s_nop 0
	v_add_f32_e32 v36, 1.0, v65
	v_rcp_f32_e32 v65, v36
	v_mfma_f32_16x16x32_bf16 v[38:41], v[152:155], v[100:103], v[40:43]
	v_mul_f32_e64 v36, v52, v56
	v_mul_f32_e64 v37, v53, v57
	v_cvt_pk_bf16_f32 v36, v36, v37
	v_pk_mul_f32 v[42:43], v[58:59], v[64:65]
	v_mfma_f32_16x16x32_bf16 v[44:47], v[148:151], v[100:103], v[44:47]
	v_mul_f32_e64 v42, v54, v42
	v_mul_f32_e64 v43, v55, v43
	v_cvt_pk_bf16_f32 v37, v42, v43
	global_store_dwordx4 v[158:159], v[34:37], off
	v_mfma_f32_16x16x32_bf16 v[52:55], v[144:147], v[104:107], v[184:187]
	s_nop 0
	v_or_b32_e32 v34, 16, v2
	v_mad_i64_i32 v[42:43], s[2:3], v34, s24, v[32:33]
	v_mul_f32_e32 v34, 0xbfb8aa3b, v48
	v_mul_f32_e32 v35, 0xbfb8aa3b, v49
	v_exp_f32_e32 v34, v34
	v_exp_f32_e32 v35, v35
	v_mul_f32_e32 v36, 0xbfb8aa3b, v50
	v_mul_f32_e32 v37, 0xbfb8aa3b, v51
	v_add_f32_e32 v34, 1.0, v34
	v_add_f32_e32 v35, 1.0, v35
	v_rcp_f32_e32 v34, v34
	v_rcp_f32_e32 v35, v35
	v_exp_f32_e32 v36, v36
	v_exp_f32_e32 v37, v37
	v_mfma_f32_16x16x32_bf16 v[24:27], v[72:75], v[76:79], v[24:27]
	v_mul_f32_e64 v34, v48, v34
	v_mul_f32_e64 v35, v49, v35
	v_add_f32_e32 v36, 1.0, v36
	v_add_f32_e32 v37, 1.0, v37
	v_pk_mul_f32 v[34:35], v[44:45], v[34:35]
	v_rcp_f32_e32 v36, v36
	v_rcp_f32_e32 v37, v37
	v_cvt_pk_bf16_f32 v34, v34, v35
	v_mul_f32_e32 v35, 0xbfb8aa3b, v60
	v_exp_f32_e32 v44, v35
	v_mul_f32_e32 v35, 0xbfb8aa3b, v61
	v_exp_f32_e32 v45, v35
	v_pk_mul_f32 v[36:37], v[50:51], v[36:37]
	v_mfma_f32_16x16x32_bf16 v[28:31], v[84:87], v[76:79], v[28:31]
	v_mul_f32_e64 v36, v46, v36
	v_mul_f32_e64 v37, v47, v37
	v_cvt_pk_bf16_f32 v35, v36, v37
	v_add_f32_e32 v36, 1.0, v44
	v_add_f32_e32 v37, 1.0, v45
	v_mul_f32_e32 v44, 0xbfb8aa3b, v62
	v_mul_f32_e32 v45, 0xbfb8aa3b, v63
	v_exp_f32_e32 v44, v44
	v_exp_f32_e32 v45, v45
	v_rcp_f32_e32 v36, v36
	v_rcp_f32_e32 v37, v37
	v_add_f32_e32 v44, 1.0, v44
	v_add_f32_e32 v45, 1.0, v45
	v_rcp_f32_e32 v44, v44
	v_rcp_f32_e32 v45, v45
	v_pk_mul_f32 v[36:37], v[60:61], v[36:37]
	v_mfma_f32_16x16x32_bf16 v[24:27], v[148:151], v[104:107], v[24:27]
	v_mul_f32_e64 v36, v38, v36
	v_mul_f32_e64 v37, v39, v37
	v_pk_mul_f32 v[38:39], v[62:63], v[44:45]
	v_cvt_pk_bf16_f32 v36, v36, v37
	v_pk_mul_f32 v[38:39], v[40:41], v[38:39]
	v_mfma_f32_16x16x32_bf16 v[28:31], v[80:83], v[104:107], v[28:31]
	v_cvt_pk_bf16_f32 v37, v38, v39
	global_store_dwordx4 v[42:43], v[34:37], off
	v_mul_f32_e32 v38, 0xbfb8aa3b, v54
	v_mul_f32_e32 v39, 0xbfb8aa3b, v55
	v_mul_f32_e32 v35, 0xbfb8aa3b, v52
	v_exp_f32_e32 v36, v35
	v_mul_f32_e32 v35, 0xbfb8aa3b, v53
	v_exp_f32_e32 v37, v35
	v_exp_f32_e32 v38, v38
	v_exp_f32_e32 v39, v39
	v_add_f32_e32 v36, 1.0, v36
	v_add_f32_e32 v37, 1.0, v37
	v_rcp_f32_e32 v36, v36
	v_rcp_f32_e32 v37, v37
	v_add_f32_e32 v38, 1.0, v38
	v_add_f32_e32 v39, 1.0, v39
	v_rcp_f32_e32 v38, v38
	v_rcp_f32_e32 v39, v39
	v_pk_mul_f32 v[36:37], v[52:53], v[36:37]
	v_mfma_f32_16x16x32_bf16 v[20:23], v[88:91], v[76:79], v[20:23]
	v_mul_f32_e64 v24, v24, v36
	v_mul_f32_e64 v25, v25, v37
	v_pk_mul_f32 v[36:37], v[54:55], v[38:39]
	v_cvt_pk_bf16_f32 v24, v24, v25
	v_mul_f32_e32 v25, 0xbfb8aa3b, v28
	v_pk_mul_f32 v[26:27], v[26:27], v[36:37]
	v_exp_f32_e32 v36, v25
	v_mul_f32_e32 v25, 0xbfb8aa3b, v29
	v_exp_f32_e32 v37, v25
	v_cvt_pk_bf16_f32 v25, v26, v27
	v_add_f32_e32 v26, 1.0, v36
	v_mul_f32_e32 v36, 0xbfb8aa3b, v30
	v_add_f32_e32 v27, 1.0, v37
	v_mul_f32_e32 v37, 0xbfb8aa3b, v31
	v_exp_f32_e32 v36, v36
	v_exp_f32_e32 v37, v37
	v_mfma_f32_16x16x32_bf16 v[16:19], v[68:71], v[92:95], v[16:19]
	v_rcp_f32_e32 v26, v26
	v_rcp_f32_e32 v27, v27
	v_add_f32_e32 v36, 1.0, v36
	v_mfma_f32_16x16x32_bf16 v[20:23], v[152:155], v[104:107], v[20:23]
	v_add_f32_e32 v37, 1.0, v37
	v_rcp_f32_e32 v36, v36
	v_rcp_f32_e32 v37, v37
	v_mfma_f32_16x16x32_bf16 v[16:19], v[144:147], v[140:143], v[16:19]
	v_mul_f32_e64 v26, v28, v26
	v_mul_f32_e64 v27, v29, v27
	v_or_b32_e32 v34, 32, v2
	s_nop 0
	v_pk_mul_f32 v[20:21], v[20:21], v[26:27]
	v_or_b32_e32 v2, 48, v2
	v_cvt_pk_bf16_f32 v26, v20, v21
	v_pk_mul_f32 v[20:21], v[30:31], v[36:37]
	v_mad_i64_i32 v[34:35], s[2:3], v34, s24, v[32:33]
	v_pk_mul_f32 v[20:21], v[22:23], v[20:21]
	v_mfma_f32_16x16x32_bf16 v[12:15], v[72:75], v[92:95], v[12:15]
	v_cvt_pk_bf16_f32 v27, v20, v21
	v_mul_f32_e32 v20, 0xbfb8aa3b, v16
	v_exp_f32_e32 v22, v20
	v_mul_f32_e32 v20, 0xbfb8aa3b, v17
	v_exp_f32_e32 v23, v20
	v_mad_i64_i32 v[20:21], s[2:3], v2, s24, v[32:33]
	v_add_f32_e32 v2, 1.0, v22
	v_rcp_f32_e32 v22, v2
	v_add_f32_e32 v2, 1.0, v23
	v_mul_f32_e32 v23, 0xbfb8aa3b, v18
	global_store_dwordx4 v[34:35], v[24:27], off
	v_mfma_f32_16x16x32_bf16 v[8:11], v[84:87], v[92:95], v[8:11]
	s_nop 0
	v_exp_f32_e32 v24, v23
	v_mul_f32_e32 v23, 0xbfb8aa3b, v19
	v_exp_f32_e32 v25, v23
	v_rcp_f32_e32 v23, v2
	v_add_f32_e32 v2, 1.0, v24
	v_mfma_f32_16x16x32_bf16 v[12:15], v[148:151], v[140:143], v[12:15]
	v_rcp_f32_e32 v24, v2
	v_add_f32_e32 v2, 1.0, v25
	v_rcp_f32_e32 v25, v2
	v_mfma_f32_16x16x32_bf16 v[8:11], v[80:83], v[140:143], v[8:11]
	v_mul_f32_e64 v16, v16, v22
	v_mul_f32_e64 v17, v17, v23
	s_nop 1
	v_pk_mul_f32 v[12:13], v[12:13], v[16:17]
	v_pk_mul_f32 v[16:17], v[18:19], v[24:25]
	v_cvt_pk_bf16_f32 v12, v12, v13
	s_nop 0
	v_mul_f32_e32 v2, 0xbfb8aa3b, v8
	v_exp_f32_e32 v2, v2
	v_mul_f32_e32 v13, 0xbfb8aa3b, v9
	v_pk_mul_f32 v[14:15], v[14:15], v[16:17]
	v_exp_f32_e32 v16, v13
	v_cvt_pk_bf16_f32 v13, v14, v15
	v_add_f32_e32 v2, 1.0, v2
	v_mul_f32_e32 v15, 0xbfb8aa3b, v10
	v_rcp_f32_e32 v14, v2
	v_add_f32_e32 v2, 1.0, v16
	v_exp_f32_e32 v16, v15
	v_mul_f32_e32 v15, 0xbfb8aa3b, v11
	v_mfma_f32_16x16x32_bf16 v[4:7], v[88:91], v[92:95], v[4:7]
	v_exp_f32_e32 v17, v15
	v_rcp_f32_e32 v15, v2
	v_add_f32_e32 v2, 1.0, v16
	v_mfma_f32_16x16x32_bf16 v[4:7], v[152:155], v[140:143], v[4:7]
	v_rcp_f32_e32 v16, v2
	v_add_f32_e32 v2, 1.0, v17
	v_rcp_f32_e32 v17, v2
	v_pk_mul_f32 v[8:9], v[8:9], v[14:15]
	s_nop 3
	v_pk_mul_f32 v[4:5], v[4:5], v[8:9]
	s_nop 0
	v_cvt_pk_bf16_f32 v14, v4, v5
	v_pk_mul_f32 v[4:5], v[10:11], v[16:17]
	s_nop 0
	v_pk_mul_f32 v[4:5], v[6:7], v[4:5]
	s_nop 0
	v_cvt_pk_bf16_f32 v15, v4, v5
	global_store_dwordx4 v[20:21], v[12:15], off
	s_cbranch_scc0 .LBB0_110

; template <int EPI>
; __device__ __forceinline__ void gemm_tile(const bf16_t* __restrict__ A, const int lda, const bf16_t* __restrict__ Bt, const int ldb,
;                                           const int K, const int m0, const int n0, void* Cout, const int ldc, char* lds, const int tid) {
;     ...
;   for (int kt = 0; kt < nt; ++kt) {
;     asm volatile("s_waitcnt vmcnt(0)" ::: "memory");
;     __syncthreads();
;     if (kt + 1 < nt) stageB(kt + 1, (kt + 1) & 1);
;     const char* sa = lds + (kt & 1) * 32768;
;     const char* sb = sa + 16384;
;     bf16x8 af[2][4], bfr[2][4];
; #pragma unroll
;     for (int ks = 0; ks < 2; ++ks) {
; #pragma unroll
;       for (int m = 0; m < 4; ++m) af[ks][m] = *(const bf16x8*)(sa + (wr * 64 + m * 16 + fr) * 128 + (ks ? xk1 : xk0));
; #pragma unroll
;       for (int n = 0; n < 4; ++n) bfr[ks][n] = *(const bf16x8*)(sb + (wc * 64 + n * 16 + fr) * 128 + (ks ? xk1 : xk0));
;     }
;     if (kt + 1 < nt) stageA(kt + 1, (kt + 1) & 1);
; #pragma unroll
;     for (int ks = 0; ks < 2; ++ks)
; #pragma unroll
;       for (int m = 0; m < 4; ++m)
; #pragma unroll
;         for (int n = 0; n < 4; ++n) acc[m][n] = __builtin_amdgcn_mfma_f32_16x16x32_bf16(bfr[ks][n], af[ks][m], acc[m][n], 0, 0, 0);
;   }
.LBB0_125:
	s_add_i32 s25, s26, 0x8000
	s_and_b32 s23, s25, 0x8000
	v_add_u32_e32 v139, s23, v176
	v_add_u32_e32 v70, 0x4000, v139
	v_lshl_add_u64 v[68:69], v[140:141], 0, s[34:35]
	v_readfirstlane_b32 s27, v70
	v_add_u32_e32 v70, 0x5000, v139
	s_mov_b32 m0, s27
	v_readfirstlane_b32 s27, v70
	v_add_u32_e32 v70, 0x6000, v139
	s_waitcnt vmcnt(0)
	s_waitcnt vmcnt(0) lgkmcnt(0)
	s_barrier
	global_load_lds_dwordx4 v[68:69], off
	v_lshl_add_u64 v[68:69], v[142:143], 0, s[34:35]
	s_mov_b32 m0, s27
	v_readfirstlane_b32 s27, v70
	v_add_u32_e32 v70, 0x7000, v139
	global_load_lds_dwordx4 v[68:69], off
	v_lshl_add_u64 v[68:69], v[144:145], 0, s[34:35]
	s_mov_b32 m0, s27
	v_readfirstlane_b32 s27, v70
	global_load_lds_dwordx4 v[68:69], off
	v_lshl_add_u64 v[68:69], v[146:147], 0, s[34:35]
	s_mov_b32 m0, s27
	s_and_b32 s26, s26, 0x8000
	global_load_lds_dwordx4 v[68:69], off
	v_or_b32_e32 v68, s26, v174
	v_add_u32_e32 v69, v68, v181
	v_add_u32_e32 v68, v68, v180
	v_or_b32_e32 v72, s26, v175
	v_readfirstlane_b32 s26, v139
	v_add_u32_e32 v168, 0x1000, v139
	ds_read_b128 v[104:107], v69
	ds_read_b128 v[100:103], v69 offset:2048
	ds_read_b128 v[96:99], v69 offset:4096
	ds_read_b128 v[84:87], v69 offset:6144
	ds_read_b128 v[184:187], v68 offset:16384
	ds_read_b128 v[188:191], v68 offset:18432
	ds_read_b128 v[192:195], v68 offset:20480
	ds_read_b128 v[196:199], v68 offset:22528
	v_add_u32_e32 v68, v72, v181
	v_add_u32_e32 v76, v72, v180
	v_lshl_add_u64 v[158:159], v[148:149], 0, s[34:35]
	s_mov_b32 m0, s26
	v_readfirstlane_b32 s26, v168
	v_add_u32_e32 v168, 0x2000, v139
	ds_read_b128 v[200:203], v68
	ds_read_b128 v[204:207], v68 offset:2048
	ds_read_b128 v[92:95], v68 offset:4096
	ds_read_b128 v[68:71], v68 offset:6144
	ds_read_b128 v[88:91], v76 offset:16384
	ds_read_b128 v[80:83], v76 offset:18432
	ds_read_b128 v[72:75], v76 offset:20480
	ds_read_b128 v[76:79], v76 offset:22528
	global_load_lds_dwordx4 v[158:159], off
	v_lshl_add_u64 v[158:159], v[150:151], 0, s[34:35]
	s_mov_b32 m0, s26
	v_readfirstlane_b32 s26, v168
	v_add_u32_e32 v139, 0x3000, v139
	global_load_lds_dwordx4 v[158:159], off
	v_lshl_add_u64 v[158:159], v[152:153], 0, s[34:35]
	s_mov_b32 m0, s26
	v_readfirstlane_b32 s26, v139
	global_load_lds_dwordx4 v[158:159], off
	v_lshl_add_u64 v[158:159], v[154:155], 0, s[34:35]
	s_mov_b32 m0, s26
	s_waitcnt lgkmcnt(0)
	s_setprio 2
	v_mfma_f32_16x16x32_bf16 v[64:67], v[184:187], v[104:107], v[64:67]
	global_load_lds_dwordx4 v[158:159], off
	s_add_u32 s34, s34, 0x80
	v_mfma_f32_16x16x32_bf16 v[60:63], v[188:191], v[104:107], v[60:63]
	s_addc_u32 s35, s35, 0
	s_cmpk_eq_i32 s34, 0x780
	s_mov_b32 s26, s25
	v_mfma_f32_16x16x32_bf16 v[56:59], v[192:195], v[104:107], v[56:59]
	v_mfma_f32_16x16x32_bf16 v[52:55], v[196:199], v[104:107], v[52:55]
	v_mfma_f32_16x16x32_bf16 v[36:39], v[184:187], v[100:103], v[36:39]
	v_mfma_f32_16x16x32_bf16 v[28:31], v[188:191], v[100:103], v[28:31]
	v_mfma_f32_16x16x32_bf16 v[20:23], v[192:195], v[100:103], v[20:23]
	v_mfma_f32_16x16x32_bf16 v[24:27], v[196:199], v[100:103], v[24:27]
	v_mfma_f32_16x16x32_bf16 v[8:11], v[184:187], v[96:99], v[8:11]
	v_mfma_f32_16x16x32_bf16 v[16:19], v[188:191], v[96:99], v[16:19]
	v_mfma_f32_16x16x32_bf16 v[32:35], v[192:195], v[96:99], v[32:35]
	v_mfma_f32_16x16x32_bf16 v[48:51], v[196:199], v[96:99], v[48:51]
	v_mfma_f32_16x16x32_bf16 v[44:47], v[184:187], v[84:87], v[44:47]
	v_mfma_f32_16x16x32_bf16 v[40:43], v[188:191], v[84:87], v[40:43]
	v_mfma_f32_16x16x32_bf16 v[12:15], v[192:195], v[84:87], v[12:15]
	v_mfma_f32_16x16x32_bf16 v[4:7], v[196:199], v[84:87], v[4:7]
	v_mfma_f32_16x16x32_bf16 v[64:67], v[88:91], v[200:203], v[64:67]
	v_mfma_f32_16x16x32_bf16 v[60:63], v[80:83], v[200:203], v[60:63]
	v_mfma_f32_16x16x32_bf16 v[56:59], v[72:75], v[200:203], v[56:59]
	v_mfma_f32_16x16x32_bf16 v[52:55], v[76:79], v[200:203], v[52:55]
	v_mfma_f32_16x16x32_bf16 v[36:39], v[88:91], v[204:207], v[36:39]
	v_mfma_f32_16x16x32_bf16 v[28:31], v[80:83], v[204:207], v[28:31]
	v_mfma_f32_16x16x32_bf16 v[20:23], v[72:75], v[204:207], v[20:23]
	v_mfma_f32_16x16x32_bf16 v[24:27], v[76:79], v[204:207], v[24:27]
	v_mfma_f32_16x16x32_bf16 v[8:11], v[88:91], v[92:95], v[8:11]
	v_mfma_f32_16x16x32_bf16 v[16:19], v[80:83], v[92:95], v[16:19]
	v_mfma_f32_16x16x32_bf16 v[32:35], v[72:75], v[92:95], v[32:35]
	v_mfma_f32_16x16x32_bf16 v[48:51], v[76:79], v[92:95], v[48:51]
	v_mfma_f32_16x16x32_bf16 v[44:47], v[88:91], v[68:71], v[44:47]
	v_mfma_f32_16x16x32_bf16 v[40:43], v[80:83], v[68:71], v[40:43]
	v_mfma_f32_16x16x32_bf16 v[12:15], v[72:75], v[68:71], v[12:15]
	v_mfma_f32_16x16x32_bf16 v[4:7], v[76:79], v[68:71], v[4:7]
	s_setprio 0
	s_cbranch_scc0 .LBB0_125
	v_add_u32_e32 v84, s23, v174
	v_add_u32_e32 v80, v84, v181
	s_waitcnt vmcnt(0)
	s_waitcnt vmcnt(0) lgkmcnt(0)
	s_barrier
; template <int EPI>
; __device__ __forceinline__ void gemm_tile(const bf16_t* __restrict__ A, const int lda, const bf16_t* __restrict__ Bt, const int ldb,
;                                           const int K, const int m0, const int n0, void* Cout, const int ldc, char* lds, const int tid) {
;     ...
;     for (int ks = 0; ks < 2; ++ks)
; #pragma unroll
;       for (int m = 0; m < 4; ++m)
; #pragma unroll
;         for (int n = 0; n < 4; ++n) acc[m][n] = __builtin_amdgcn_mfma_f32_16x16x32_bf16(bfr[ks][n], af[ks][m], acc[m][n], 0, 0, 0);
;   }
;   if (EPI == EPI_RESID) {
;     float* C0 = (float*)Cout + (size_t)(m0 + wr * 64 + fr) * ldc + n0 + wc * 64 + fq * 4;
; #pragma unroll
;     for (int mh = 0; mh < 2; ++mh) {
;       f32x4 xin[2][4];
; #pragma unroll
;       for (int m = 0; m < 2; ++m)
; #pragma unroll
;         for (int n = 0; n < 4; ++n) xin[m][n] = *(const f32x4*)(C0 + (size_t)(mh * 2 + m) * 16 * ldc + n * 16);
	ds_read_b128 v[68:71], v80
	ds_read_b128 v[72:75], v80 offset:2048
	ds_read_b128 v[76:79], v80 offset:4096
	ds_read_b128 v[80:83], v80 offset:6144
	v_add_u32_e32 v96, v84, v180
	ds_read_b128 v[84:87], v96 offset:16384
	ds_read_b128 v[88:91], v96 offset:18432
	ds_read_b128 v[92:95], v96 offset:20480
	ds_read_b128 v[96:99], v96 offset:22528
	v_add_u32_e32 v139, s23, v175
	v_add_u32_e32 v144, v139, v181
	s_waitcnt lgkmcnt(3)
	v_mfma_f32_16x16x32_bf16 v[36:39], v[84:87], v[72:75], v[36:39]
	ds_read_b128 v[100:103], v144
	ds_read_b128 v[104:107], v144 offset:2048
	ds_read_b128 v[140:143], v144 offset:4096
	ds_read_b128 v[144:147], v144 offset:6144
	v_add_u32_e32 v139, v139, v180
	ds_read_b128 v[148:151], v139 offset:16384
	ds_read_b128 v[152:155], v139 offset:18432
	ds_read_b128 v[184:187], v139 offset:20480
	ds_read_b128 v[188:191], v139 offset:22528
	v_mfma_f32_16x16x32_bf16 v[64:67], v[84:87], v[68:71], v[64:67]
	v_readlane_b32 s26, v253, 25
	v_readlane_b32 s27, v253, 26
	v_mov_b32_e32 v139, v3
	s_waitcnt lgkmcnt(10)
	v_mfma_f32_16x16x32_bf16 v[60:63], v[88:91], v[68:71], v[60:63]
	s_add_i32 s24, s24, s0
	s_waitcnt lgkmcnt(9)
	v_mfma_f32_16x16x32_bf16 v[56:59], v[92:95], v[68:71], v[56:59]
	s_waitcnt lgkmcnt(8)
	v_mfma_f32_16x16x32_bf16 v[52:55], v[96:99], v[68:71], v[52:55]
	v_mfma_f32_16x16x32_bf16 v[8:11], v[84:87], v[76:79], v[8:11]
	v_mfma_f32_16x16x32_bf16 v[16:19], v[88:91], v[76:79], v[16:19]
	v_mfma_f32_16x16x32_bf16 v[68:71], v[92:95], v[76:79], v[32:35]
	v_mfma_f32_16x16x32_bf16 v[48:51], v[96:99], v[76:79], v[48:51]
	s_waitcnt lgkmcnt(3)
	v_mfma_f32_16x16x32_bf16 v[76:79], v[148:151], v[104:107], v[36:39]
	s_nop 2
	v_add_u32_e32 v36, s3, v182
	v_ashrrev_i32_e32 v37, 31, v36
	v_lshlrev_b64 v[36:37], 12, v[36:37]
	v_mfma_f32_16x16x32_bf16 v[20:23], v[92:95], v[72:75], v[20:23]
	v_lshl_add_u64 v[36:37], s[26:27], 0, v[36:37]
	s_ashr_i32 s3, s2, 31
	v_lshl_add_u64 v[36:37], s[2:3], 2, v[36:37]
	v_mfma_f32_16x16x32_bf16 v[28:31], v[88:91], v[72:75], v[28:31]
	v_lshl_add_u64 v[36:37], v[36:37], 0, v[2:3]
	v_lshl_add_u64 v[36:37], v[36:37], 0, v[138:139]
	s_mov_b32 s2, 0x10000
	v_mfma_f32_16x16x32_bf16 v[24:27], v[96:99], v[72:75], v[24:27]
	s_cmpk_gt_i32 s24, 0x427
	v_mfma_f32_16x16x32_bf16 v[44:47], v[84:87], v[80:83], v[44:47]
	v_mfma_f32_16x16x32_bf16 v[40:43], v[88:91], v[80:83], v[40:43]
	v_mfma_f32_16x16x32_bf16 v[72:75], v[92:95], v[80:83], v[12:15]
	s_waitcnt lgkmcnt(1)
	v_mfma_f32_16x16x32_bf16 v[84:87], v[184:187], v[104:107], v[20:23]
	s_waitcnt lgkmcnt(0)
	v_mfma_f32_16x16x32_bf16 v[20:23], v[188:191], v[140:143], v[48:51]
	s_nop 2
	v_add_co_u32_e32 v50, vcc, s2, v36
	v_mfma_f32_16x16x32_bf16 v[4:7], v[96:99], v[80:83], v[4:7]
	s_nop 0
	v_addc_co_u32_e32 v51, vcc, 0, v37, vcc
	s_mov_b32 s2, 0x20000
	v_mfma_f32_16x16x32_bf16 v[64:67], v[148:151], v[100:103], v[64:67]
	v_mfma_f32_16x16x32_bf16 v[60:63], v[152:155], v[100:103], v[60:63]
	v_mfma_f32_16x16x32_bf16 v[56:59], v[184:187], v[100:103], v[56:59]
	v_mfma_f32_16x16x32_bf16 v[52:55], v[188:191], v[100:103], v[52:55]
	v_mfma_f32_16x16x32_bf16 v[80:83], v[152:155], v[104:107], v[28:31]
	v_mfma_f32_16x16x32_bf16 v[88:91], v[188:191], v[104:107], v[24:27]
	v_mfma_f32_16x16x32_bf16 v[32:35], v[148:151], v[140:143], v[8:11]
	v_mfma_f32_16x16x32_bf16 v[28:31], v[152:155], v[140:143], v[16:19]
	v_mfma_f32_16x16x32_bf16 v[24:27], v[184:187], v[140:143], v[68:71]
	v_mfma_f32_16x16x32_bf16 v[16:19], v[148:151], v[144:147], v[44:47]
	v_mfma_f32_16x16x32_bf16 v[12:15], v[152:155], v[144:147], v[40:43]
	s_nop 2
	global_load_dwordx4 v[38:41], v[36:37], off
	global_load_dwordx4 v[42:45], v[36:37], off offset:64
	global_load_dwordx4 v[46:49], v[36:37], off offset:128
	global_load_dwordx4 v[68:71], v[36:37], off offset:192
	v_mfma_f32_16x16x32_bf16 v[8:11], v[184:187], v[144:147], v[72:75]
	s_nop 2
	global_load_dwordx4 v[72:75], v[50:51], off
	global_load_dwordx4 v[92:95], v[50:51], off offset:64
	global_load_dwordx4 v[96:99], v[50:51], off offset:128
	global_load_dwordx4 v[100:103], v[50:51], off offset:192
	s_waitcnt vmcnt(7)
; template <int EPI>
; __device__ __forceinline__ void gemm_tile(const bf16_t* __restrict__ A, const int lda, const bf16_t* __restrict__ Bt, const int ldb,
;                                           const int K, const int m0, const int n0, void* Cout, const int ldc, char* lds, const int tid) {
;     ...
;     float* C0 = (float*)Cout + (size_t)(m0 + wr * 64 + fr) * ldc + n0 + wc * 64 + fq * 4;
; #pragma unroll
;     for (int mh = 0; mh < 2; ++mh) {
;       f32x4 xin[2][4];
; #pragma unroll
;       for (int m = 0; m < 2; ++m)
; #pragma unroll
;         for (int n = 0; n < 4; ++n) xin[m][n] = *(const f32x4*)(C0 + (size_t)(mh * 2 + m) * 16 * ldc + n * 16);
; #pragma unroll
;       for (int m = 0; m < 2; ++m)
; #pragma unroll
;         for (int n = 0; n < 4; ++n) asm volatile("" : "+v"(xin[m][n]));
; #pragma unroll
;       for (int m = 0; m < 2; ++m)
; #pragma unroll
;         for (int n = 0; n < 4; ++n) *(f32x4*)(C0 + (size_t)(mh * 2 + m) * 16 * ldc + n * 16) = xin[m][n] * ALPHA + acc[mh * 2 + m][n];
;     }
;     return;
	s_nop 0
	v_pk_fma_f32 v[40:41], v[40:41], s[78:79], v[66:67] op_sel_hi:[1,0,1]
	v_pk_fma_f32 v[38:39], v[38:39], s[78:79], v[64:65] op_sel_hi:[1,0,1]
	s_waitcnt vmcnt(6)
	s_waitcnt vmcnt(5)
	s_waitcnt vmcnt(4)
	s_waitcnt vmcnt(3)
	s_waitcnt vmcnt(2)
	s_waitcnt vmcnt(1)
	s_waitcnt vmcnt(0)
	global_store_dwordx4 v[36:37], v[38:41], off
	v_mfma_f32_16x16x32_bf16 v[4:7], v[188:191], v[144:147], v[4:7]
	s_nop 0
	v_fma_f32 v40, v44, s78, v62
	v_fma_f32 v41, v45, s78, v63
	v_pk_fma_f32 v[38:39], v[42:43], s[78:79], v[60:61] op_sel_hi:[1,0,1]
	global_store_dwordx4 v[36:37], v[38:41], off offset:64
	s_nop 1
	v_pk_fma_f32 v[40:41], v[48:49], s[78:79], v[58:59] op_sel_hi:[1,0,1]
	v_pk_fma_f32 v[38:39], v[46:47], s[78:79], v[56:57] op_sel_hi:[1,0,1]
	global_store_dwordx4 v[36:37], v[38:41], off offset:128
	s_nop 1
	v_pk_fma_f32 v[40:41], v[70:71], s[78:79], v[54:55] op_sel_hi:[1,0,1]
	v_pk_fma_f32 v[38:39], v[68:69], s[78:79], v[52:53] op_sel_hi:[1,0,1]
	global_store_dwordx4 v[36:37], v[38:41], off offset:192
	v_add_co_u32_e32 v70, vcc, s2, v36
	s_nop 0
	v_pk_fma_f32 v[40:41], v[74:75], s[78:79], v[78:79] op_sel_hi:[1,0,1]
	v_pk_fma_f32 v[38:39], v[72:73], s[78:79], v[76:77] op_sel_hi:[1,0,1]
	global_store_dwordx4 v[50:51], v[38:41], off
	v_addc_co_u32_e32 v71, vcc, 0, v37, vcc
	s_nop 0
	v_pk_fma_f32 v[40:41], v[94:95], s[78:79], v[82:83] op_sel_hi:[1,0,1]
	v_pk_fma_f32 v[38:39], v[92:93], s[78:79], v[80:81] op_sel_hi:[1,0,1]
	global_store_dwordx4 v[50:51], v[38:41], off offset:64
	s_mov_b32 s2, 0x30000
	v_add_co_u32_e32 v36, vcc, s2, v36
	v_pk_fma_f32 v[40:41], v[98:99], s[78:79], v[86:87] op_sel_hi:[1,0,1]
	v_pk_fma_f32 v[38:39], v[96:97], s[78:79], v[84:85] op_sel_hi:[1,0,1]
	global_store_dwordx4 v[50:51], v[38:41], off offset:128
	v_addc_co_u32_e32 v37, vcc, 0, v37, vcc
	s_nop 0
	v_pk_fma_f32 v[40:41], v[102:103], s[78:79], v[90:91] op_sel_hi:[1,0,1]
	v_pk_fma_f32 v[38:39], v[100:101], s[78:79], v[88:89] op_sel_hi:[1,0,1]
	global_store_dwordx4 v[50:51], v[38:41], off offset:192
	global_load_dwordx4 v[38:41], v[70:71], off
	s_nop 0
	global_load_dwordx4 v[42:45], v[70:71], off offset:64
	global_load_dwordx4 v[46:49], v[70:71], off offset:128
	global_load_dwordx4 v[50:53], v[70:71], off offset:192
	global_load_dwordx4 v[54:57], v[36:37], off
	global_load_dwordx4 v[58:61], v[36:37], off offset:64
	global_load_dwordx4 v[62:65], v[36:37], off offset:128
	global_load_dwordx4 v[66:69], v[36:37], off offset:192
	s_waitcnt vmcnt(7)
	s_waitcnt vmcnt(6)
	s_waitcnt vmcnt(5)
	s_waitcnt vmcnt(4)
	s_waitcnt vmcnt(3)
	s_waitcnt vmcnt(2)
	s_waitcnt vmcnt(1)
	s_waitcnt vmcnt(0)
	v_pk_fma_f32 v[34:35], v[40:41], s[78:79], v[34:35] op_sel_hi:[1,0,1]
	v_pk_fma_f32 v[32:33], v[38:39], s[78:79], v[32:33] op_sel_hi:[1,0,1]
	v_pk_fma_f32 v[30:31], v[44:45], s[78:79], v[30:31] op_sel_hi:[1,0,1]
	v_pk_fma_f32 v[28:29], v[42:43], s[78:79], v[28:29] op_sel_hi:[1,0,1]
	v_pk_fma_f32 v[26:27], v[48:49], s[78:79], v[26:27] op_sel_hi:[1,0,1]
	v_pk_fma_f32 v[24:25], v[46:47], s[78:79], v[24:25] op_sel_hi:[1,0,1]
	v_pk_fma_f32 v[22:23], v[52:53], s[78:79], v[22:23] op_sel_hi:[1,0,1]
	v_pk_fma_f32 v[20:21], v[50:51], s[78:79], v[20:21] op_sel_hi:[1,0,1]
	v_pk_fma_f32 v[18:19], v[56:57], s[78:79], v[18:19] op_sel_hi:[1,0,1]
	v_pk_fma_f32 v[16:17], v[54:55], s[78:79], v[16:17] op_sel_hi:[1,0,1]
	v_pk_fma_f32 v[14:15], v[60:61], s[78:79], v[14:15] op_sel_hi:[1,0,1]
	v_pk_fma_f32 v[12:13], v[58:59], s[78:79], v[12:13] op_sel_hi:[1,0,1]
	v_pk_fma_f32 v[10:11], v[64:65], s[78:79], v[10:11] op_sel_hi:[1,0,1]
	v_pk_fma_f32 v[8:9], v[62:63], s[78:79], v[8:9] op_sel_hi:[1,0,1]
	v_pk_fma_f32 v[6:7], v[68:69], s[78:79], v[6:7] op_sel_hi:[1,0,1]
	v_pk_fma_f32 v[4:5], v[66:67], s[78:79], v[4:5] op_sel_hi:[1,0,1]
	global_store_dwordx4 v[70:71], v[32:35], off
	global_store_dwordx4 v[70:71], v[28:31], off offset:64
	global_store_dwordx4 v[70:71], v[24:27], off offset:128
	global_store_dwordx4 v[70:71], v[20:23], off offset:192
	global_store_dwordx4 v[36:37], v[16:19], off
	global_store_dwordx4 v[36:37], v[12:15], off offset:64
	global_store_dwordx4 v[36:37], v[8:11], off offset:128
	global_store_dwordx4 v[36:37], v[4:7], off offset:192
	s_cbranch_scc0 .LBB0_124

; template <int EPI>
; __device__ __forceinline__ void gemm_tile(const bf16_t* __restrict__ A, const int lda, const bf16_t* __restrict__ Bt, const int ldb,
;                                           const int K, const int m0, const int n0, void* Cout, const int ldc, char* lds, const int tid) {
;     ...
;   for (int kt = 0; kt < nt; ++kt) {
;     asm volatile("s_waitcnt vmcnt(0)" ::: "memory");
;     __syncthreads();
;     if (kt + 1 < nt) stageB(kt + 1, (kt + 1) & 1);
;     const char* sa = lds + (kt & 1) * 32768;
;     const char* sb = sa + 16384;
;     bf16x8 af[2][4], bfr[2][4];
; #pragma unroll
;     for (int ks = 0; ks < 2; ++ks) {
; #pragma unroll
;       for (int m = 0; m < 4; ++m) af[ks][m] = *(const bf16x8*)(sa + (wr * 64 + m * 16 + fr) * 128 + (ks ? xk1 : xk0));
; #pragma unroll
;       for (int n = 0; n < 4; ++n) bfr[ks][n] = *(const bf16x8*)(sb + (wc * 64 + n * 16 + fr) * 128 + (ks ? xk1 : xk0));
;     }
;     if (kt + 1 < nt) stageA(kt + 1, (kt + 1) & 1);
; #pragma unroll
;     for (int ks = 0; ks < 2; ++ks)
; #pragma unroll
;       for (int m = 0; m < 4; ++m)
; #pragma unroll
;         for (int n = 0; n < 4; ++n) acc[m][n] = __builtin_amdgcn_mfma_f32_16x16x32_bf16(bfr[ks][n], af[ks][m], acc[m][n], 0, 0, 0);
;   }
.LBB0_649:
	s_add_i32 s24, s25, 0x8000
	s_and_b32 s26, s24, 0x8000
	v_add_u32_e32 v2, s26, v177
	v_add_u32_e32 v70, 0x4000, v2
	v_lshl_add_u64 v[68:69], v[140:141], 0, s[34:35]
	v_readfirstlane_b32 s26, v70
	v_add_u32_e32 v70, 0x5000, v2
	s_mov_b32 m0, s26
	v_readfirstlane_b32 s26, v70
	v_add_u32_e32 v70, 0x6000, v2
	s_waitcnt vmcnt(0)
	s_waitcnt vmcnt(0) lgkmcnt(0)
	s_barrier
	global_load_lds_dwordx4 v[68:69], off
	v_lshl_add_u64 v[68:69], v[142:143], 0, s[34:35]
	s_mov_b32 m0, s26
	v_readfirstlane_b32 s26, v70
	v_add_u32_e32 v70, 0x7000, v2
	global_load_lds_dwordx4 v[68:69], off
	v_lshl_add_u64 v[68:69], v[144:145], 0, s[34:35]
	s_mov_b32 m0, s26
	v_readfirstlane_b32 s26, v70
	global_load_lds_dwordx4 v[68:69], off
	v_lshl_add_u64 v[68:69], v[146:147], 0, s[34:35]
	s_mov_b32 m0, s26
	s_and_b32 s25, s25, 0x8000
	global_load_lds_dwordx4 v[68:69], off
	v_or_b32_e32 v68, s25, v175
	v_add_u32_e32 v69, v68, v182
	v_add_u32_e32 v68, v68, v181
	v_or_b32_e32 v72, s25, v176
	v_readfirstlane_b32 s25, v2
	v_add_u32_e32 v158, 0x1000, v2
	ds_read_b128 v[104:107], v69
	ds_read_b128 v[100:103], v69 offset:2048
	ds_read_b128 v[96:99], v69 offset:4096
	ds_read_b128 v[84:87], v69 offset:6144
	ds_read_b128 v[184:187], v68 offset:16384
	ds_read_b128 v[188:191], v68 offset:18432
	ds_read_b128 v[192:195], v68 offset:20480
	ds_read_b128 v[196:199], v68 offset:22528
	v_add_u32_e32 v68, v72, v182
	v_add_u32_e32 v76, v72, v181
	v_lshl_add_u64 v[208:209], v[148:149], 0, s[34:35]
	s_mov_b32 m0, s25
	v_readfirstlane_b32 s25, v158
	v_add_u32_e32 v158, 0x2000, v2
	ds_read_b128 v[200:203], v68
	ds_read_b128 v[204:207], v68 offset:2048
	ds_read_b128 v[92:95], v68 offset:4096
	ds_read_b128 v[68:71], v68 offset:6144
	ds_read_b128 v[88:91], v76 offset:16384
	ds_read_b128 v[80:83], v76 offset:18432
	ds_read_b128 v[72:75], v76 offset:20480
	ds_read_b128 v[76:79], v76 offset:22528
	global_load_lds_dwordx4 v[208:209], off
	v_lshl_add_u64 v[208:209], v[150:151], 0, s[34:35]
	s_mov_b32 m0, s25
	v_readfirstlane_b32 s25, v158
	v_add_u32_e32 v2, 0x3000, v2
	global_load_lds_dwordx4 v[208:209], off
	v_lshl_add_u64 v[208:209], v[152:153], 0, s[34:35]
	s_mov_b32 m0, s25
	v_readfirstlane_b32 s25, v2
	global_load_lds_dwordx4 v[208:209], off
	v_lshl_add_u64 v[208:209], v[154:155], 0, s[34:35]
	s_mov_b32 m0, s25
	s_waitcnt lgkmcnt(0)
	s_setprio 2
	v_mfma_f32_16x16x32_bf16 v[64:67], v[184:187], v[104:107], v[64:67]
	global_load_lds_dwordx4 v[208:209], off
	s_add_u32 s34, s34, 0x80
	v_mfma_f32_16x16x32_bf16 v[60:63], v[188:191], v[104:107], v[60:63]
	s_addc_u32 s35, s35, 0
	s_cmpk_lg_i32 s34, 0x780
	s_mov_b32 s25, s24
	v_mfma_f32_16x16x32_bf16 v[56:59], v[192:195], v[104:107], v[56:59]
	v_mfma_f32_16x16x32_bf16 v[44:47], v[196:199], v[104:107], v[44:47]
	v_mfma_f32_16x16x32_bf16 v[36:39], v[184:187], v[100:103], v[36:39]
	v_mfma_f32_16x16x32_bf16 v[28:31], v[188:191], v[100:103], v[28:31]
	v_mfma_f32_16x16x32_bf16 v[12:15], v[192:195], v[100:103], v[12:15]
	v_mfma_f32_16x16x32_bf16 v[24:27], v[196:199], v[100:103], v[24:27]
	v_mfma_f32_16x16x32_bf16 v[8:11], v[184:187], v[96:99], v[8:11]
	v_mfma_f32_16x16x32_bf16 v[20:23], v[188:191], v[96:99], v[20:23]
	v_mfma_f32_16x16x32_bf16 v[32:35], v[192:195], v[96:99], v[32:35]
	v_mfma_f32_16x16x32_bf16 v[52:55], v[196:199], v[96:99], v[52:55]
	v_mfma_f32_16x16x32_bf16 v[48:51], v[184:187], v[84:87], v[48:51]
	v_mfma_f32_16x16x32_bf16 v[40:43], v[188:191], v[84:87], v[40:43]
	v_mfma_f32_16x16x32_bf16 v[16:19], v[192:195], v[84:87], v[16:19]
	v_mfma_f32_16x16x32_bf16 v[4:7], v[196:199], v[84:87], v[4:7]
	v_mfma_f32_16x16x32_bf16 v[64:67], v[88:91], v[200:203], v[64:67]
	v_mfma_f32_16x16x32_bf16 v[60:63], v[80:83], v[200:203], v[60:63]
	v_mfma_f32_16x16x32_bf16 v[56:59], v[72:75], v[200:203], v[56:59]
	v_mfma_f32_16x16x32_bf16 v[44:47], v[76:79], v[200:203], v[44:47]
	v_mfma_f32_16x16x32_bf16 v[36:39], v[88:91], v[204:207], v[36:39]
	v_mfma_f32_16x16x32_bf16 v[28:31], v[80:83], v[204:207], v[28:31]
	v_mfma_f32_16x16x32_bf16 v[12:15], v[72:75], v[204:207], v[12:15]
	v_mfma_f32_16x16x32_bf16 v[24:27], v[76:79], v[204:207], v[24:27]
	v_mfma_f32_16x16x32_bf16 v[8:11], v[88:91], v[92:95], v[8:11]
	v_mfma_f32_16x16x32_bf16 v[20:23], v[80:83], v[92:95], v[20:23]
	v_mfma_f32_16x16x32_bf16 v[32:35], v[72:75], v[92:95], v[32:35]
	v_mfma_f32_16x16x32_bf16 v[52:55], v[76:79], v[92:95], v[52:55]
	v_mfma_f32_16x16x32_bf16 v[48:51], v[88:91], v[68:71], v[48:51]
	v_mfma_f32_16x16x32_bf16 v[40:43], v[80:83], v[68:71], v[40:43]
	v_mfma_f32_16x16x32_bf16 v[16:19], v[72:75], v[68:71], v[16:19]
	v_mfma_f32_16x16x32_bf16 v[4:7], v[76:79], v[68:71], v[4:7]
	s_setprio 0
	s_cbranch_scc1 .LBB0_649
	v_add_u32_e32 v2, v175, v181
	s_waitcnt vmcnt(0)
	s_waitcnt vmcnt(0) lgkmcnt(0)
	s_barrier
; __device__ __forceinline__ unsigned pk2(float lo, float hi) { const f32x2_t v = {lo, hi}; const bf16x2_t b = __builtin_convertvector(v, bf16x2_t); return __builtin_bit_cast(unsigned, b); }
; template <int EPI>
; __device__ __forceinline__ void gemm_tile(const bf16_t* __restrict__ A, const int lda, const bf16_t* __restrict__ Bt, const int ldb,
;                                           const int K, const int m0, const int n0, void* Cout, const int ldc, char* lds, const int tid) {
;     ...
;     for (int ks = 0; ks < 2; ++ks)
; #pragma unroll
;       for (int m = 0; m < 4; ++m)
; #pragma unroll
;         for (int n = 0; n < 4; ++n) acc[m][n] = __builtin_amdgcn_mfma_f32_16x16x32_bf16(bfr[ks][n], af[ks][m], acc[m][n], 0, 0, 0);
;     ...
; #pragma unroll
;   for (int m = 0; m < 4; ++m) {
;     const int row = m0 + wr * 64 + m * 16 + fr;
;     if (EPI == EPI_BF16) {
;       bf16_t* C = (bf16_t*)Cout + (size_t)row * ldc + n0 + wc * 64 + fq * 8;
; #pragma unroll
;       for (int pq = 0; pq < 2; ++pq) { uint4 o; o.x = pk2(acc[m][2 * pq][0], acc[m][2 * pq][1]); o.y = pk2(acc[m][2 * pq][2], acc[m][2 * pq][3]);
;         o.z = pk2(acc[m][2 * pq + 1][0], acc[m][2 * pq + 1][1]); o.w = pk2(acc[m][2 * pq + 1][2], acc[m][2 * pq + 1][3]); *(uint4*)(C + pq * 32) = o; }
	ds_read_b128 v[68:71], v2 offset:49152
	v_add_u32_e32 v92, v175, v182
	ds_read_b128 v[72:75], v2 offset:51200
	ds_read_b128 v[76:79], v92 offset:32768
	ds_read_b128 v[80:83], v92 offset:34816
	ds_read_b128 v[84:87], v2 offset:53248
	ds_read_b128 v[88:91], v2 offset:55296
	s_waitcnt lgkmcnt(3)
	v_mfma_f32_16x16x32_bf16 v[64:67], v[68:71], v[76:79], v[64:67]
	v_add_u32_e32 v2, v176, v182
	v_add_u32_e32 v104, v176, v181
	s_add_i32 s23, s23, s0
	v_mfma_f32_16x16x32_bf16 v[60:63], v[72:75], v[76:79], v[60:63]
	s_waitcnt lgkmcnt(1)
	v_mfma_f32_16x16x32_bf16 v[56:59], v[84:87], v[76:79], v[56:59]
	s_waitcnt lgkmcnt(0)
	v_mfma_f32_16x16x32_bf16 v[44:47], v[88:91], v[76:79], v[44:47]
	v_mfma_f32_16x16x32_bf16 v[36:39], v[68:71], v[80:83], v[36:39]
	v_mfma_f32_16x16x32_bf16 v[28:31], v[72:75], v[80:83], v[28:31]
	v_mfma_f32_16x16x32_bf16 v[12:15], v[84:87], v[80:83], v[12:15]
	v_mfma_f32_16x16x32_bf16 v[24:27], v[88:91], v[80:83], v[24:27]
	ds_read_b128 v[76:79], v92 offset:36864
	ds_read_b128 v[80:83], v92 offset:38912
	s_waitcnt lgkmcnt(1)
	v_mfma_f32_16x16x32_bf16 v[8:11], v[68:71], v[76:79], v[8:11]
	v_mfma_f32_16x16x32_bf16 v[20:23], v[72:75], v[76:79], v[20:23]
	v_mfma_f32_16x16x32_bf16 v[32:35], v[84:87], v[76:79], v[32:35]
	v_mfma_f32_16x16x32_bf16 v[52:55], v[88:91], v[76:79], v[52:55]
	s_waitcnt lgkmcnt(0)
	v_mfma_f32_16x16x32_bf16 v[48:51], v[68:71], v[80:83], v[48:51]
	ds_read_b128 v[68:71], v2 offset:32768
	ds_read_b128 v[76:79], v2 offset:34816
	ds_read_b128 v[92:95], v104 offset:49152
	v_mfma_f32_16x16x32_bf16 v[40:43], v[72:75], v[80:83], v[40:43]
	ds_read_b128 v[72:75], v2 offset:36864
	ds_read_b128 v[96:99], v2 offset:38912
	ds_read_b128 v[100:103], v104 offset:51200
	v_or_b32_e32 v2, s3, v131
	v_add_u32_e32 v2, v2, v183
	v_mfma_f32_16x16x32_bf16 v[16:19], v[84:87], v[80:83], v[16:19]
	ds_read_b128 v[84:87], v104 offset:53248
	ds_read_b128 v[104:107], v104 offset:55296
	s_ashr_i32 s3, s2, 31
	v_lshl_add_u64 v[140:141], s[2:3], 1, v[134:135]
	s_waitcnt lgkmcnt(1)
	v_mfma_f32_16x16x32_bf16 v[56:59], v[84:87], v[68:71], v[56:59]
	v_mad_i64_i32 v[142:143], s[2:3], v2, s68, v[140:141]
	s_cmpk_gt_i32 s23, 0x101a
	s_waitcnt lgkmcnt(0)
	v_mfma_f32_16x16x32_bf16 v[44:47], v[104:107], v[68:71], v[44:47]
	s_nop 3
	v_cvt_pk_bf16_f32 v56, v56, v57
	v_cvt_pk_bf16_f32 v57, v58, v59
	v_mfma_f32_16x16x32_bf16 v[12:15], v[84:87], v[76:79], v[12:15]
	v_mfma_f32_16x16x32_bf16 v[24:27], v[104:107], v[76:79], v[24:27]
	v_cvt_pk_bf16_f32 v58, v44, v45
	v_or_b32_e32 v44, 16, v2
	v_mad_i64_i32 v[44:45], s[2:3], v44, s68, v[140:141]
	s_nop 3
	v_cvt_pk_bf16_f32 v12, v12, v13
	v_cvt_pk_bf16_f32 v13, v14, v15
	v_cvt_pk_bf16_f32 v14, v24, v25
	v_cvt_pk_bf16_f32 v15, v26, v27
	v_mfma_f32_16x16x32_bf16 v[8:11], v[92:95], v[72:75], v[8:11]
	global_store_dwordx4 v[44:45], v[12:15], off offset:64
	v_or_b32_e32 v24, 32, v2
	v_mad_i64_i32 v[24:25], s[2:3], v24, s68, v[140:141]
	v_mfma_f32_16x16x32_bf16 v[12:15], v[100:103], v[72:75], v[20:23]
	s_nop 3
	v_cvt_pk_bf16_f32 v8, v8, v9
	v_cvt_pk_bf16_f32 v9, v10, v11
	v_or_b32_e32 v2, 48, v2
	v_mfma_f32_16x16x32_bf16 v[20:23], v[84:87], v[72:75], v[32:35]
	v_cvt_pk_bf16_f32 v59, v46, v47
	v_cvt_pk_bf16_f32 v10, v12, v13
	v_cvt_pk_bf16_f32 v11, v14, v15
	global_store_dwordx4 v[24:25], v[8:11], off
	v_mfma_f32_16x16x32_bf16 v[4:7], v[88:91], v[80:83], v[4:7]
	s_nop 2
	v_cvt_pk_bf16_f32 v12, v20, v21
	v_cvt_pk_bf16_f32 v13, v22, v23
	v_mad_i64_i32 v[20:21], s[2:3], v2, s68, v[140:141]
	v_mfma_f32_16x16x32_bf16 v[8:11], v[104:107], v[72:75], v[52:55]
	global_store_dwordx4 v[142:143], v[56:59], off offset:64
	v_mfma_f32_16x16x32_bf16 v[64:67], v[92:95], v[68:71], v[64:67]
	v_mfma_f32_16x16x32_bf16 v[60:63], v[100:103], v[68:71], v[60:63]
	s_nop 4
	v_cvt_pk_bf16_f32 v14, v8, v9
	v_cvt_pk_bf16_f32 v15, v10, v11
	global_store_dwordx4 v[24:25], v[12:15], off offset:64
	v_mfma_f32_16x16x32_bf16 v[8:11], v[92:95], v[96:99], v[48:51]
	v_cvt_pk_bf16_f32 v64, v64, v65
	v_cvt_pk_bf16_f32 v65, v66, v67
	v_cvt_pk_bf16_f32 v66, v60, v61
	v_mfma_f32_16x16x32_bf16 v[12:15], v[100:103], v[96:99], v[40:43]
	v_cvt_pk_bf16_f32 v67, v62, v63
	s_nop 2
	v_cvt_pk_bf16_f32 v8, v8, v9
	v_cvt_pk_bf16_f32 v9, v10, v11
	v_mfma_f32_16x16x32_bf16 v[36:39], v[92:95], v[76:79], v[36:39]
	global_store_dwordx4 v[142:143], v[64:67], off
	v_cvt_pk_bf16_f32 v10, v12, v13
	v_cvt_pk_bf16_f32 v11, v14, v15
	v_mfma_f32_16x16x32_bf16 v[28:31], v[100:103], v[76:79], v[28:31]
	global_store_dwordx4 v[20:21], v[8:11], off
	s_nop 2
	v_cvt_pk_bf16_f32 v36, v36, v37
	v_cvt_pk_bf16_f32 v37, v38, v39
	v_mfma_f32_16x16x32_bf16 v[12:15], v[84:87], v[96:99], v[16:19]
	v_mfma_f32_16x16x32_bf16 v[4:7], v[104:107], v[96:99], v[4:7]
	v_cvt_pk_bf16_f32 v38, v28, v29
	v_cvt_pk_bf16_f32 v39, v30, v31
	s_nop 4
	v_cvt_pk_bf16_f32 v8, v12, v13
	v_cvt_pk_bf16_f32 v9, v14, v15
	global_store_dwordx4 v[44:45], v[36:39], off
	v_cvt_pk_bf16_f32 v10, v4, v5
	v_cvt_pk_bf16_f32 v11, v6, v7
	global_store_dwordx4 v[20:21], v[8:11], off offset:64
	s_cbranch_scc0 .LBB0_648
